# baseline (speedup 1.0000x reference)
; #define PIN(i) ((const float*)pget(p, (i)))
; __device__ __forceinline__ int opaque_tid() { int t = threadIdx.x; asm volatile("" : "+v"(t)); return t; }
; __device__ __forceinline__ void sample_out_gemm(const bf16_t* __restrict__ H  , const bf16_t* __restrict__ Wt  , const float* __restrict__ xs, float* __restrict__ ys, char* lds) {
;     const int tid = opaque_tid(), wid = tid >> 6, lane = tid & 63, r32 = lane & 31, hi = lane >> 5;
;     float* red = (float*)lds;
;     for (int it = blockIdx.x; it < 256; it += gridDim.x) {
;         const int rb = it >> 6, cb = it & 63;
;         const bf16_t* ap = H + (size_t)(rb * 32 + r32) * 2048 + wid * 256 + hi * 8;
;         const bf16_t* bp = Wt + (size_t)(cb * 32 + r32) * 2048 + wid * 256 + hi * 8;
; __global__ void __launch_bounds__(NTH, 2) mega(Params p) {
;     ...
;             EpiOut E; E.xp = l == 0 ? PIN(I_XP) : POUT + O_Y; E.xs = l == 0 ? PIN(I_XS) : POUT + O_Y + (size_t)TP * 2048; E.out = POUT + O_Y;
;     ...
; #pragma unroll 1
;             for (int rep = 0; rep < (l == 0 ? DUP_G4 : 1); ++rep) gemm_phase<false>(lds, S, E);
;             sample_out_gemm((const bf16_t*)(ws + WS_H) + (size_t)TP * 2048, (const bf16_t*)(ws + WS_WOUT), l == 0 ? PIN(I_XS) : POUT + O_Y + (size_t)TP * 2048, POUT + O_Y + (size_t)TP * 2048, (char*)lds_raw);
.LBB0_346:
	s_nop 0
	v_readlane_b32 s4, v246, 38
	v_readlane_b32 s5, v246, 39
	s_and_b64 vcc, exec, s[4:5]
	s_cbranch_vccz .LBB0_377
	v_readlane_b32 s4, v247, 61
	s_nop 3
	s_bitcmp1_b32 s4, 0
	s_cbranch_scc0 .Lso_skipfirst
	s_add_i32 s4, s56, 6
	s_cmp_gt_u32 s4, 12
	s_cbranch_scc1 .Lso_l1
	s_load_dwordx2 s[6:7], s[0:1], 0x8
	s_branch .Lso_go
.Lso_l1:
	s_load_dwordx2 s[6:7], s[0:1], 0xb8
	s_waitcnt lgkmcnt(0)
	s_add_u32 s6, s6, 0x8000000
	s_addc_u32 s7, s7, 0
.Lso_go:
	s_waitcnt lgkmcnt(0)
	v_readlane_b32 s4, v249, 8
	v_readlane_b32 s5, v249, 9
	s_mov_b32 s8, 23
	v_mov_b32_e32 v0, v159
	s_andn2_b64 vcc, exec, s[4:5]
	s_cbranch_vccnz .Lso_done
	s_ashr_i32 s9, s8, 31
	s_lshl_b64 s[4:5], s[8:9], 3
	s_add_u32 s4, s0, s4
	s_addc_u32 s5, s1, s5
	s_load_dwordx2 s[4:5], s[4:5], 0x0
	v_and_b32_e32 v2, 63, v0
	v_ashrrev_i32_e32 v7, 6, v0
	v_lshl_add_u32 v25, v2, 2, 0
	v_lshlrev_b32_e32 v2, 8, v7
	s_waitcnt lgkmcnt(0)
	s_add_u32 s8, s4, 0x8000000
	s_addc_u32 s9, s5, 0
	v_ashrrev_i32_e32 v3, 31, v2
	v_readlane_b32 s4, v249, 38
	v_lshlrev_b64 v[2:3], 1, v[2:3]
	v_readlane_b32 s5, v249, 39
	v_bfe_u32 v6, v0, 5, 1
	v_and_b32_e32 v24, 31, v0
	v_lshl_add_u64 v[4:5], s[4:5], 0, v[2:3]
	v_readlane_b32 s4, v248, 32
	v_readlane_b32 s5, v248, 33
	v_lshlrev_b32_e32 v0, 4, v6
	v_lshl_add_u64 v[18:19], v[4:5], 0, v[0:1]
	v_lshl_add_u64 v[2:3], s[4:5], 0, v[2:3]
	v_lshl_add_u64 v[20:21], v[2:3], 0, v[0:1]
	v_lshlrev_b32_e32 v2, 1, v7
	v_lshlrev_b32_e32 v3, 2, v7
	v_and_b32_e32 v3, -8, v3
	v_lshlrev_b32_e32 v4, 2, v6
	v_lshlrev_b32_e32 v26, 9, v7
	v_and_b32_e32 v2, 2, v2
	v_lshlrev_b32_e32 v0, 12, v7
	v_or3_b32 v22, v3, v2, v4
	v_or_b32_e32 v2, 0x100, v26
	v_readlane_b32 s10, v247, 61
	v_ashrrev_i32_e32 v23, 31, v22
	v_add_u32_e32 v27, v25, v0
	v_add_u32_e32 v28, v25, v2
	v_readlane_b32 s4, v247, 63
	s_mov_b32 s5, s10
	v_readlane_b32 s11, v247, 62
; __device__ __forceinline__ int crow(int r, int hi) { return (r & 3) + 8 * (r >> 2) + 4 * hi; }
; __device__ __forceinline__ void sample_out_gemm(const bf16_t* __restrict__ H  , const bf16_t* __restrict__ Wt  , const float* __restrict__ xs, float* __restrict__ ys, char* lds) {
;     ...
;     for (int it = blockIdx.x; it < 256; it += gridDim.x) {
;         const int rb = it >> 6, cb = it & 63;
;         const bf16_t* ap = H + (size_t)(rb * 32 + r32) * 2048 + wid * 256 + hi * 8;
;         const bf16_t* bp = Wt + (size_t)(cb * 32 + r32) * 2048 + wid * 256 + hi * 8;
;         bf16x8 af[16], bfr[16];
; #pragma unroll
;         for (int k = 0; k < 16; ++k) { af[k] = *(const bf16x8*)(ap + k * 16); bfr[k] = *(const bf16x8*)(bp + k * 16); }
;         f32x16 acc = {};
; #pragma unroll
;         for (int k = 0; k < 16; ++k) acc = __builtin_amdgcn_mfma_f32_32x32x16_bf16(bfr[k], af[k], acc, 0, 0, 0);
;         __syncthreads();
; #pragma unroll
;         for (int r = 0; r < 16; ++r) red[(wid * 16 + r) * 64 + lane] = acc[r];
;         __syncthreads();
; #pragma unroll
;         for (int rr = 0; rr < 2; ++rr) { const int r = wid * 2 + rr; float sum = 0.f;
; #pragma unroll
;             for (int w = 0; w < 8; ++w) sum += red[(w * 16 + r) * 64 + lane];
;             const size_t o = (size_t)(rb * 32 + r32) * 2048 + cb * 32 + crow(r, hi);
;             ys[o] = xs[o] + sum; }
;     }
.Lso_loop:
	s_ashr_i32 s10, s5, 1
	s_andn2_b32 s10, s10, 31
	s_and_b32 s11, s4, 0x7e0
	v_or_b32_e32 v98, s10, v24
	v_or_b32_e32 v0, s11, v24
	v_ashrrev_i32_e32 v99, 31, v98
	v_lshlrev_b32_e32 v0, 12, v0
	v_lshlrev_b64 v[8:9], 12, v[98:99]
	v_lshl_add_u64 v[6:7], v[20:21], 0, v[0:1]
	v_lshl_add_u64 v[100:101], v[18:19], 0, v[8:9]
	global_load_dwordx4 v[2:5], v[6:7], off
	global_load_dwordx4 v[30:33], v[6:7], off offset:32
	global_load_dwordx4 v[34:37], v[6:7], off offset:64
	global_load_dwordx4 v[38:41], v[6:7], off offset:96
	global_load_dwordx4 v[42:45], v[6:7], off offset:128
	global_load_dwordx4 v[46:49], v[6:7], off offset:160
	global_load_dwordx4 v[50:53], v[6:7], off offset:192
	global_load_dwordx4 v[54:57], v[6:7], off offset:224
	global_load_dwordx4 v[58:61], v[6:7], off offset:256
	global_load_dwordx4 v[62:65], v[6:7], off offset:288
	global_load_dwordx4 v[66:69], v[6:7], off offset:320
	global_load_dwordx4 v[70:73], v[6:7], off offset:352
	global_load_dwordx4 v[74:77], v[6:7], off offset:384
	global_load_dwordx4 v[78:81], v[6:7], off offset:416
	global_load_dwordx4 v[82:85], v[6:7], off offset:448
	global_load_dwordx4 v[86:89], v[6:7], off offset:480
	s_nop 0
	global_load_dwordx4 v[6:9], v[100:101], off
	global_load_dwordx4 v[90:93], v[100:101], off offset:32
	global_load_dwordx4 v[94:97], v[100:101], off offset:64
	v_add_u32_e32 v0, v25, v26
	s_add_i32 s5, s5, s74
	s_add_i32 s4, s4, s45
	s_cmpk_gt_i32 s5, 0xff
	s_waitcnt vmcnt(2)
	v_mfma_f32_32x32x16_bf16 v[2:17], v[2:5], v[6:9], 0
	s_waitcnt vmcnt(1)
	v_mfma_f32_32x32x16_bf16 v[2:17], v[30:33], v[90:93], v[2:17]
	global_load_dwordx4 v[30:33], v[100:101], off offset:96
	s_waitcnt vmcnt(1)
	v_mfma_f32_32x32x16_bf16 v[2:17], v[34:37], v[94:97], v[2:17]
	global_load_dwordx4 v[34:37], v[100:101], off offset:128
	s_waitcnt vmcnt(1)
	v_mfma_f32_32x32x16_bf16 v[2:17], v[38:41], v[30:33], v[2:17]
	global_load_dwordx4 v[30:33], v[100:101], off offset:160
	v_lshlrev_b64 v[38:39], 11, v[98:99]
	v_or_b32_e32 v38, s11, v38
	s_waitcnt vmcnt(1)
	v_mfma_f32_32x32x16_bf16 v[2:17], v[42:45], v[34:37], v[2:17]
	global_load_dwordx4 v[34:37], v[100:101], off offset:192
	s_waitcnt vmcnt(1)
	v_mfma_f32_32x32x16_bf16 v[2:17], v[46:49], v[30:33], v[2:17]
	global_load_dwordx4 v[30:33], v[100:101], off offset:224
	s_waitcnt vmcnt(1)
	v_mfma_f32_32x32x16_bf16 v[2:17], v[50:53], v[34:37], v[2:17]
	global_load_dwordx4 v[34:37], v[100:101], off offset:256
	s_waitcnt vmcnt(1)
	v_mfma_f32_32x32x16_bf16 v[2:17], v[54:57], v[30:33], v[2:17]
	global_load_dwordx4 v[30:33], v[100:101], off offset:288
	s_waitcnt vmcnt(1)
	v_mfma_f32_32x32x16_bf16 v[2:17], v[58:61], v[34:37], v[2:17]
	global_load_dwordx4 v[34:37], v[100:101], off offset:320
	s_waitcnt vmcnt(1)
	v_mfma_f32_32x32x16_bf16 v[2:17], v[62:65], v[30:33], v[2:17]
	global_load_dwordx4 v[30:33], v[100:101], off offset:352
	s_waitcnt vmcnt(1)
	v_mfma_f32_32x32x16_bf16 v[2:17], v[66:69], v[34:37], v[2:17]
	global_load_dwordx4 v[34:37], v[100:101], off offset:384
	s_waitcnt vmcnt(1)
	v_mfma_f32_32x32x16_bf16 v[2:17], v[70:73], v[30:33], v[2:17]
	global_load_dwordx4 v[30:33], v[100:101], off offset:416
	s_waitcnt vmcnt(1)
	v_mfma_f32_32x32x16_bf16 v[2:17], v[74:77], v[34:37], v[2:17]
	global_load_dwordx4 v[34:37], v[100:101], off offset:448
	s_waitcnt vmcnt(1)
	v_mfma_f32_32x32x16_bf16 v[2:17], v[78:81], v[30:33], v[2:17]
	global_load_dwordx4 v[30:33], v[100:101], off offset:480
	s_barrier
	s_waitcnt vmcnt(1)
	v_mfma_f32_32x32x16_bf16 v[2:17], v[82:85], v[34:37], v[2:17]
	v_lshl_add_u64 v[34:35], v[38:39], 0, v[22:23]
	v_lshlrev_b64 v[34:35], 2, v[34:35]
	v_lshl_add_u64 v[36:37], s[6:7], 0, v[34:35]
	s_waitcnt vmcnt(0)
	v_mfma_f32_32x32x16_bf16 v[2:17], v[86:89], v[30:33], v[2:17]
	s_nop 11
	ds_write2st64_b32 v27, v2, v3 offset1:1
	ds_write2st64_b32 v27, v4, v5 offset0:2 offset1:3
	ds_write2st64_b32 v27, v6, v7 offset0:4 offset1:5
	ds_write2st64_b32 v27, v8, v9 offset0:6 offset1:7
	ds_write2st64_b32 v27, v10, v11 offset0:8 offset1:9
	ds_write2st64_b32 v27, v12, v13 offset0:10 offset1:11
	ds_write2st64_b32 v27, v14, v15 offset0:12 offset1:13
	ds_write2st64_b32 v27, v16, v17 offset0:14 offset1:15
	s_waitcnt lgkmcnt(0)
	s_barrier
	global_load_dwordx2 v[2:3], v[36:37], off
	ds_read2st64_b32 v[6:7], v0 offset1:16
	ds_read2st64_b32 v[8:9], v0 offset0:32 offset1:48
	ds_read2st64_b32 v[10:11], v0 offset0:64 offset1:80
	ds_read2st64_b32 v[12:13], v0 offset0:96 offset1:112
	ds_read2st64_b32 v[14:15], v28 offset1:16
	ds_read2st64_b32 v[16:17], v28 offset0:32 offset1:48
	ds_read2st64_b32 v[30:31], v28 offset0:64 offset1:80
	ds_read2st64_b32 v[32:33], v28 offset0:96 offset1:112
	s_waitcnt lgkmcnt(7)
	v_add_f32_e32 v0, 0, v6
	s_waitcnt lgkmcnt(3)
	v_add_f32_e32 v6, 0, v14
	v_add_f32_e32 v0, v0, v7
	v_add_f32_e32 v6, v6, v15
	v_add_f32_e32 v0, v0, v8
	s_waitcnt lgkmcnt(2)
	v_add_f32_e32 v6, v6, v16
	v_add_f32_e32 v0, v0, v9
	v_add_f32_e32 v6, v6, v17
	v_add_f32_e32 v0, v0, v10
	s_waitcnt lgkmcnt(1)
	v_add_f32_e32 v6, v6, v30
	v_add_f32_e32 v0, v0, v11
	v_add_f32_e32 v6, v6, v31
	v_add_f32_e32 v0, v0, v12
	s_waitcnt lgkmcnt(0)
	v_add_f32_e32 v6, v6, v32
	v_add_f32_e32 v0, v0, v13
	v_add_f32_e32 v6, v6, v33
	v_lshl_add_u64 v[4:5], s[8:9], 0, v[34:35]
	s_waitcnt vmcnt(0)
	v_add_f32_e32 v2, v0, v2
	v_add_f32_e32 v3, v6, v3
	global_store_dwordx2 v[4:5], v[2:3], off
	s_cbranch_scc0 .Lso_loop
.Lso_done:
	s_waitcnt vmcnt(0) lgkmcnt(0)
	s_barrier
.Lso_skipfirst:
	s_add_i32 s4, s56, 6
	s_cmp_gt_u32 s4, 12
	s_cselect_b64 s[6:7], -1, 0
	s_mov_b64 s[10:11], -1
	s_and_b64 vcc, exec, s[6:7]
	s_cbranch_vccz .LBB0_349
	s_mov_b32 s8, 23
	s_mov_b64 s[10:11], 0

; __device__ __forceinline__ int opaque_tid() { int t = threadIdx.x; asm volatile("" : "+v"(t)); return t; }
; __device__ __forceinline__ void sample_out_gemm(const bf16_t* __restrict__ H  , const bf16_t* __restrict__ Wt  , const float* __restrict__ xs, float* __restrict__ ys, char* lds) {
;     const int tid = opaque_tid(), wid = tid >> 6, lane = tid & 63, r32 = lane & 31, hi = lane >> 5;
;     float* red = (float*)lds;
;     for (int it = blockIdx.x; it < 256; it += gridDim.x) {
;         const int rb = it >> 6, cb = it & 63;
;         const bf16_t* ap = H + (size_t)(rb * 32 + r32) * 2048 + wid * 256 + hi * 8;
;         const bf16_t* bp = Wt + (size_t)(cb * 32 + r32) * 2048 + wid * 256 + hi * 8;
.LBB0_373:
	v_readlane_b32 s4, v247, 61
	s_nop 3
	s_bitcmp1_b32 s4, 0
	s_cbranch_scc1 .LBB0_376
	v_readlane_b32 s4, v249, 8
	v_readlane_b32 s5, v249, 9
	s_mov_b32 s8, 23
	v_mov_b32_e32 v0, v159
	s_andn2_b64 vcc, exec, s[4:5]
	s_cbranch_vccnz .LBB0_376
	s_ashr_i32 s9, s8, 31
	s_lshl_b64 s[4:5], s[8:9], 3
	s_add_u32 s4, s0, s4
	s_addc_u32 s5, s1, s5
	s_load_dwordx2 s[4:5], s[4:5], 0x0
	v_and_b32_e32 v2, 63, v0
	v_ashrrev_i32_e32 v7, 6, v0
	v_lshl_add_u32 v25, v2, 2, 0
	v_lshlrev_b32_e32 v2, 8, v7
	s_waitcnt lgkmcnt(0)
	s_add_u32 s8, s4, 0x8000000
	s_addc_u32 s9, s5, 0
	v_ashrrev_i32_e32 v3, 31, v2
	v_readlane_b32 s4, v249, 38
	v_lshlrev_b64 v[2:3], 1, v[2:3]
	v_readlane_b32 s5, v249, 39
	v_bfe_u32 v6, v0, 5, 1
	v_and_b32_e32 v24, 31, v0
	v_lshl_add_u64 v[4:5], s[4:5], 0, v[2:3]
	v_readlane_b32 s4, v248, 32
	v_readlane_b32 s5, v248, 33
	v_lshlrev_b32_e32 v0, 4, v6
	v_lshl_add_u64 v[18:19], v[4:5], 0, v[0:1]
	v_lshl_add_u64 v[2:3], s[4:5], 0, v[2:3]
	v_lshl_add_u64 v[20:21], v[2:3], 0, v[0:1]
	v_lshlrev_b32_e32 v2, 1, v7
	v_lshlrev_b32_e32 v3, 2, v7
	v_and_b32_e32 v3, -8, v3
	v_lshlrev_b32_e32 v4, 2, v6
	v_lshlrev_b32_e32 v26, 9, v7
	v_and_b32_e32 v2, 2, v2
	v_lshlrev_b32_e32 v0, 12, v7
	v_or3_b32 v22, v3, v2, v4
	v_or_b32_e32 v2, 0x100, v26
	v_readlane_b32 s10, v247, 61
	v_ashrrev_i32_e32 v23, 31, v22
	v_add_u32_e32 v27, v25, v0
	v_add_u32_e32 v28, v25, v2
	v_readlane_b32 s4, v247, 63
	s_mov_b32 s5, s10
	v_readlane_b32 s11, v247, 62
